# GEMM phase prologues: stage-1 tile loads issued before the first wait+barrier (vmcnt 2->8)
# baseline (speedup 1.0000x reference)
; #define PG8_STAGE(bufoff, gbase, voff) do { _Pragma("unroll") for (int _i = 0; _i < 2; ++_i) \
;         __builtin_amdgcn_global_load_lds((const unsigned*)((const char*)(gbase) + (voff)[_i]), (LAS unsigned*)(lds + (bufoff) + ldsw + _i * 8192), 16, 0, 0); } while (0)
; #define PG8_WAIT_V(n) asm volatile("s_waitcnt vmcnt(" #n ")" ::: "memory")
; #define PG8_BAR __builtin_amdgcn_s_barrier()
; template <class EpiT, class Sched>
; __device__ __forceinline__ void gemm_phase(LAS unsigned char* lds, const Gemm g, const Sched& S, const EpiT& E, int wv) {
;     ...
;     const int foff = lds_byte(fr, fq * 8);
;     const int aoff = wr * 8192 + foff, boff = wc * 4096 + foff;
;     ...
;     const char* cA = (const char*)g.A + (size_t)cur.pm * tstepA + (size_t)(cur.pn >> g.zshift) * g.zA; const char* cB = (const char*)g.Bt + (size_t)cur.pn * tstepB;
;     PG8_STAGE(PG8_SB(0, 0), cB, voffB); PG8_STAGE(PG8_SB(0, 1), cB + hstepB, voffB); PG8_STAGE(PG8_SA(0, 0), cA, voffA); PG8_STAGE(PG8_SA(0, 1), cA + hstepA, voffA);
;     if (wr == 1) PG8_BAR;
;     PG8_WAIT_V(2); PG8_BAR;
;     PG8_STAGE(PG8_SB(1, 0), cB + kstep, voffB); PG8_STAGE(PG8_SA(1, 0), cA + kstep, voffA); PG8_STAGE(PG8_SB(1, 1), cB + hstepB + kstep, voffB);
;     PG8_WAIT_V(6); PG8_BAR;
.LBB0_240:
	s_add_u32 s10, s0, 0xa800000
	s_addc_u32 s11, s1, 0
	s_and_b32 s2, s2, 3
	s_add_i32 m0, s36, 0x18000
	v_lshl_add_u64 v[6:7], v[6:7], 0, s[92:93]
	s_lshl_b32 s5, s3, 13
	s_lshl_b32 s15, s2, 12
	global_load_lds_dwordx4 v[6:7], off
	v_lshl_add_u64 v[4:5], v[4:5], 0, s[92:93]
	s_add_i32 m0, s36, 0x1a000
	s_add_i32 s40, s36, 0x8000
	s_add_i32 s41, s36, 0xa000
	global_load_lds_dwordx4 v[4:5], off
	v_lshl_add_u64 v[2:3], v[2:3], 0, s[92:93]
	s_mov_b32 m0, s40
	s_add_u32 s12, s28, 0x40080
	global_load_lds_dwordx4 v[2:3], off
	v_lshl_add_u64 v[0:1], v[0:1], 0, s[92:93]
	s_mov_b32 m0, s41
	s_addc_u32 s13, s29, 0
	global_load_lds_dwordx4 v[0:1], off
	s_add_i32 m0, s36, 0x1c000
	v_lshl_add_u64 v[0:1], s[12:13], 0, v[192:193]
	global_load_lds_dwordx4 v[0:1], off
	v_lshl_add_u64 v[0:1], s[12:13], 0, v[140:141]
	s_add_i32 m0, s36, 0x1e000
	s_cmpk_lt_u32 s14, 0x100
	global_load_lds_dwordx4 v[0:1], off
	s_waitcnt vmcnt(8)
	s_barrier
	v_and_b32_e32 v0, 15, v8
	v_and_b32_e32 v1, 48, v8
	v_lshl_or_b32 v0, v0, 6, v1
	v_lshlrev_b32_e32 v1, 2, v8
	v_and_b32_e32 v1, 32, v1
	v_bitop3_b32 v2, v0, s5, v1 bitop3:0xde
	v_bitop3_b32 v164, s15, v0, v1 bitop3:0xf6
	v_lshlrev_b32_e32 v0, 14, v9
	v_and_b32_e32 v0, 0xffff8000, v0
	v_lshl_add_u32 v0, v10, 11, v0
	v_and_b32_e32 v1, 1, v9
	v_lshl_or_b32 v0, v1, 6, v0
	v_lshl_add_u32 v142, v11, 1, v0
	v_lshlrev_b32_e32 v0, 14, v12
	s_cselect_b64 s[12:13], -1, 0
	s_lshl_b32 s42, s3, 6
	v_and_b32_e32 v0, 0xffff8000, v0
	s_waitcnt vmcnt(6)
	s_lshl_b32 s43, s2, 5
	s_ashr_i32 s44, s42, 31
	s_lshl_b32 s2, s2, 6
	v_lshl_add_u32 v0, v13, 11, v0
	v_and_b32_e32 v1, 1, v12
	s_add_u32 s14, s10, s2
	v_lshl_or_b32 v0, v1, 6, v0
	s_addc_u32 s15, s11, 0
	v_mov_b32_e32 v143, v193
	v_lshl_add_u32 v144, v14, 1, v0
	v_mov_b32_e32 v145, v193
	s_mov_b32 s5, 0
	v_add_u32_e32 v165, 0, v2
	s_barrier
	s_branch .LBB0_243

; #define PG8_STAGE(bufoff, gbase, voff) do { _Pragma("unroll") for (int _i = 0; _i < 2; ++_i) \
;         __builtin_amdgcn_global_load_lds((const unsigned*)((const char*)(gbase) + (voff)[_i]), (LAS unsigned*)(lds + (bufoff) + ldsw + _i * 8192), 16, 0, 0); } while (0)
; #define PG8_WAIT_V(n) asm volatile("s_waitcnt vmcnt(" #n ")" ::: "memory")
; #define PG8_BAR __builtin_amdgcn_s_barrier()
; template <class EpiT, class Sched>
; __device__ __forceinline__ void gemm_phase(LAS unsigned char* lds, const Gemm g, const Sched& S, const EpiT& E, int wv) {
;     ...
;     const int foff = lds_byte(fr, fq * 8);
;     const int aoff = wr * 8192 + foff, boff = wc * 4096 + foff;
;     ...
;     const char* cA = (const char*)g.A + (size_t)cur.pm * tstepA + (size_t)(cur.pn >> g.zshift) * g.zA; const char* cB = (const char*)g.Bt + (size_t)cur.pn * tstepB;
;     PG8_STAGE(PG8_SB(0, 0), cB, voffB); PG8_STAGE(PG8_SB(0, 1), cB + hstepB, voffB); PG8_STAGE(PG8_SA(0, 0), cA, voffA); PG8_STAGE(PG8_SA(0, 1), cA + hstepA, voffA);
;     if (wr == 1) PG8_BAR;
;     PG8_WAIT_V(2); PG8_BAR;
;     PG8_STAGE(PG8_SB(1, 0), cB + kstep, voffB); PG8_STAGE(PG8_SA(1, 0), cA + kstep, voffA); PG8_STAGE(PG8_SB(1, 1), cB + hstepB + kstep, voffB);
;     PG8_WAIT_V(6); PG8_BAR;
.LBB0_461:
	s_add_u32 s22, s12, 0x11000000
	s_addc_u32 s23, s13, 0
	s_lshl_b64 s[24:25], s[76:77], 2
	s_add_u32 s24, s4, s24
	s_addc_u32 s25, s5, s25
	s_add_i32 m0, s50, 0x18000
	v_lshl_add_u64 v[0:1], v[0:1], 0, s[92:93]
	global_load_lds_dwordx4 v[0:1], off
	v_lshl_add_u64 v[0:1], v[2:3], 0, s[92:93]
	s_add_i32 m0, s50, 0x1a000
	s_add_i32 s54, s50, 0x8000
	global_load_lds_dwordx4 v[0:1], off
	v_lshl_add_u64 v[0:1], v[8:9], 0, s[92:93]
	s_mov_b32 m0, s54
	s_add_i32 s55, s50, 0xa000
	global_load_lds_dwordx4 v[0:1], off
	v_lshl_add_u64 v[0:1], v[10:11], 0, s[92:93]
	s_mov_b32 m0, s55
	s_lshr_b32 s3, s3, 26
	global_load_lds_dwordx4 v[0:1], off
	s_add_i32 m0, s50, 0x1c000
	v_lshl_add_u64 v[0:1], v[4:5], 0, s[92:93]
	global_load_lds_dwordx4 v[0:1], off
	v_lshl_add_u64 v[0:1], v[6:7], 0, s[92:93]
	s_add_i32 m0, s50, 0x1e000
	s_add_i32 s3, s2, s3
	global_load_lds_dwordx4 v[0:1], off
	s_waitcnt vmcnt(8)
	s_barrier
	v_and_b32_e32 v0, 15, v12
	v_and_b32_e32 v1, 48, v12
	v_lshl_or_b32 v0, v0, 6, v1
	v_lshlrev_b32_e32 v1, 2, v12
	s_and_b32 s56, s30, 3
	s_ashr_i32 s57, s3, 6
	v_and_b32_e32 v1, 32, v1
	s_lshl_b32 s3, s11, 13
	v_bitop3_b32 v2, v0, s3, v1 bitop3:0xde
	s_lshl_b32 s3, s56, 12
	s_cmp_gt_i32 s2, 63
	s_cselect_b64 s[26:27], -1, 0
	s_add_i32 s58, s57, -2
	s_cmpk_lt_u32 s9, 0x100
	v_bitop3_b32 v158, s3, v0, v1 bitop3:0xf6
	s_cselect_b64 s[28:29], -1, 0
	s_lshl_b32 s2, s56, 2
	v_readlane_b32 s3, v255, 22
	s_add_i32 s62, s3, s2
	s_lshl_b32 s2, s30, 5
	s_and_b32 s63, s2, 32
	s_and_b32 s2, s30, 2
	v_add_u32_e32 v0, v15, v13
	s_lshl_b32 s2, s2, 2
	v_add_lshl_u32 v0, v0, v14, 1
	v_mov_b32_e32 v1, v193
	s_waitcnt vmcnt(6)
	s_lshl_b32 s59, s11, 6
	s_add_i32 s72, s3, s2
	s_bfe_u32 s73, s30, 0x10001
	s_lshl_b32 s2, s63, 1
	v_lshl_add_u64 v[138:139], s[16:17], 0, v[0:1]
	v_add_u32_e32 v0, v18, v16
	s_add_u32 s30, s22, s2
	v_add_lshl_u32 v0, v0, v17, 1
	s_addc_u32 s31, s23, 0
	s_or_b32 s90, s56, 4
	s_ashr_i32 s91, s44, 31
	v_lshl_add_u64 v[140:141], s[16:17], 0, v[0:1]
	s_mov_b32 s67, 0
	v_add_u32_e32 v159, 0, v2
	s_barrier
	s_branch .LBB0_464

; #define PG8_STAGE(bufoff, gbase, voff) do { _Pragma("unroll") for (int _i = 0; _i < 2; ++_i) \
;         __builtin_amdgcn_global_load_lds((const unsigned*)((const char*)(gbase) + (voff)[_i]), (LAS unsigned*)(lds + (bufoff) + ldsw + _i * 8192), 16, 0, 0); } while (0)
; #define PG8_WAIT_V(n) asm volatile("s_waitcnt vmcnt(" #n ")" ::: "memory")
; #define PG8_BAR __builtin_amdgcn_s_barrier()
; template <class EpiT, class Sched>
; __device__ __forceinline__ void gemm_phase(LAS unsigned char* lds, const Gemm g, const Sched& S, const EpiT& E, int wv) {
;     ...
;     const int foff = lds_byte(fr, fq * 8);
;     const int aoff = wr * 8192 + foff, boff = wc * 4096 + foff;
;     ...
;     const char* cA = (const char*)g.A + (size_t)cur.pm * tstepA + (size_t)(cur.pn >> g.zshift) * g.zA; const char* cB = (const char*)g.Bt + (size_t)cur.pn * tstepB;
;     PG8_STAGE(PG8_SB(0, 0), cB, voffB); PG8_STAGE(PG8_SB(0, 1), cB + hstepB, voffB); PG8_STAGE(PG8_SA(0, 0), cA, voffA); PG8_STAGE(PG8_SA(0, 1), cA + hstepA, voffA);
;     if (wr == 1) PG8_BAR;
;     PG8_WAIT_V(2); PG8_BAR;
;     PG8_STAGE(PG8_SB(1, 0), cB + kstep, voffB); PG8_STAGE(PG8_SA(1, 0), cA + kstep, voffA); PG8_STAGE(PG8_SB(1, 1), cB + hstepB + kstep, voffB);
;     PG8_WAIT_V(6); PG8_BAR;
.LBB0_612:
	s_add_u32 s14, s12, 0x12b00000
	s_addc_u32 s15, s13, 0
	s_add_u32 s16, s12, 0x3200000
	s_addc_u32 s17, s13, 0
	s_lshl_b64 s[18:19], s[76:77], 2
	s_waitcnt lgkmcnt(0)
	s_add_u32 s18, s4, s18
	s_addc_u32 s19, s5, s19
	s_add_i32 m0, s46, 0x18000
	v_lshl_add_u64 v[0:1], v[0:1], 0, s[92:93]
	global_load_lds_dwordx4 v[0:1], off
	v_lshl_add_u64 v[0:1], v[2:3], 0, s[92:93]
	s_add_i32 m0, s46, 0x1a000
	s_add_i32 s50, s46, 0x8000
	global_load_lds_dwordx4 v[0:1], off
	v_lshl_add_u64 v[0:1], v[8:9], 0, s[92:93]
	s_mov_b32 m0, s50
	s_add_i32 s51, s46, 0xa000
	global_load_lds_dwordx4 v[0:1], off
	v_lshl_add_u64 v[0:1], v[10:11], 0, s[92:93]
	s_mov_b32 m0, s51
	s_lshr_b32 s3, s3, 26
	global_load_lds_dwordx4 v[0:1], off
	s_add_i32 m0, s46, 0x1c000
	v_lshl_add_u64 v[0:1], v[4:5], 0, s[92:93]
	global_load_lds_dwordx4 v[0:1], off
	v_lshl_add_u64 v[0:1], v[6:7], 0, s[92:93]
	s_add_i32 m0, s46, 0x1e000
	s_add_i32 s3, s2, s3
	global_load_lds_dwordx4 v[0:1], off
	s_waitcnt vmcnt(8)
	s_barrier
	v_and_b32_e32 v0, 15, v12
	v_and_b32_e32 v1, 48, v12
	v_lshl_or_b32 v0, v0, 6, v1
	v_lshlrev_b32_e32 v1, 2, v12
	s_and_b32 s4, s26, 3
	s_ashr_i32 s52, s3, 6
	v_and_b32_e32 v1, 32, v1
	s_lshl_b32 s3, s24, 13
	v_bitop3_b32 v2, v0, s3, v1 bitop3:0xde
	s_lshl_b32 s3, s4, 12
	s_cmp_gt_i32 s2, 63
	s_cselect_b64 s[20:21], -1, 0
	s_add_i32 s53, s52, -2
	s_cmpk_lt_u32 s22, 0x100
	s_cselect_b64 s[22:23], -1, 0
	s_lshl_b32 s2, s4, 2
	s_add_i32 s55, s2, 0
	s_lshl_b32 s54, s24, 6
	s_add_i32 s55, s55, 0x20400
	s_cmp_lt_u32 s4, 2
	s_cselect_b64 s[24:25], -1, 0
	s_lshl_b32 s2, s26, 5
	s_and_b32 s56, s2, 32
	s_cmp_eq_u32 s4, 2
	s_cselect_b64 s[26:27], -1, 0
	s_ashr_i32 s57, s40, 31
	s_lshl_b32 s2, s4, 6
	s_add_u32 s28, s14, s2
	v_bitop3_b32 v158, s3, v0, v1 bitop3:0xf6
	s_addc_u32 s29, s15, 0
	v_add_u32_e32 v0, v15, v13
	s_add_u32 s2, s12, s2
	v_add_lshl_u32 v0, v0, v14, 1
	v_mov_b32_e32 v1, v193
	s_waitcnt vmcnt(6)
	s_addc_u32 s3, s13, 0
	v_lshl_add_u64 v[146:147], s[6:7], 0, v[0:1]
	v_add_u32_e32 v0, v18, v16
	s_add_u32 s12, s2, 0x14600000
	v_add_lshl_u32 v0, v0, v17, 1
	s_addc_u32 s13, s3, 0
	v_lshl_add_u64 v[148:149], s[6:7], 0, v[0:1]
	s_mov_b32 s58, 0
	v_add_u32_e32 v159, 0, v2
	s_barrier
	s_branch .LBB0_615

; #define PG8_STAGE(bufoff, gbase, voff) do { _Pragma("unroll") for (int _i = 0; _i < 2; ++_i) \
;         __builtin_amdgcn_global_load_lds((const unsigned*)((const char*)(gbase) + (voff)[_i]), (LAS unsigned*)(lds + (bufoff) + ldsw + _i * 8192), 16, 0, 0); } while (0)
; #define PG8_WAIT_V(n) asm volatile("s_waitcnt vmcnt(" #n ")" ::: "memory")
; #define PG8_BAR __builtin_amdgcn_s_barrier()
; template <class EpiT, class Sched>
; __device__ __forceinline__ void gemm_phase(LAS unsigned char* lds, const Gemm g, const Sched& S, const EpiT& E, int wv) {
;     ...
;     const int foff = lds_byte(fr, fq * 8);
;     const int aoff = wr * 8192 + foff, boff = wc * 4096 + foff;
;     ...
;     const char* cA = (const char*)g.A + (size_t)cur.pm * tstepA + (size_t)(cur.pn >> g.zshift) * g.zA; const char* cB = (const char*)g.Bt + (size_t)cur.pn * tstepB;
;     PG8_STAGE(PG8_SB(0, 0), cB, voffB); PG8_STAGE(PG8_SB(0, 1), cB + hstepB, voffB); PG8_STAGE(PG8_SA(0, 0), cA, voffA); PG8_STAGE(PG8_SA(0, 1), cA + hstepA, voffA);
;     if (wr == 1) PG8_BAR;
;     PG8_WAIT_V(2); PG8_BAR;
;     PG8_STAGE(PG8_SB(1, 0), cB + kstep, voffB); PG8_STAGE(PG8_SA(1, 0), cA + kstep, voffA); PG8_STAGE(PG8_SB(1, 1), cB + hstepB + kstep, voffB);
;     PG8_WAIT_V(6); PG8_BAR;
.LBB0_1036:
	s_add_u32 s6, s2, 0xd100000
	s_addc_u32 s7, s3, 0
	s_add_u32 s8, s2, 0x16a00000
	s_addc_u32 s9, s3, 0
	s_and_b32 s1, s11, 3
	s_add_i32 m0, s21, 0x18000
	v_lshl_add_u64 v[6:7], v[6:7], 0, s[92:93]
	s_lshl_b32 s11, s12, 13
	s_lshl_b32 s13, s1, 12
	global_load_lds_dwordx4 v[6:7], off
	v_lshl_add_u64 v[4:5], v[4:5], 0, s[92:93]
	s_add_i32 m0, s21, 0x1a000
	s_add_i32 s48, s21, 0x8000
	s_add_i32 s49, s21, 0xa000
	global_load_lds_dwordx4 v[4:5], off
	v_lshl_add_u64 v[0:1], v[0:1], 0, s[92:93]
	s_mov_b32 m0, s48
	s_add_u32 s2, s24, 0x20080
	global_load_lds_dwordx4 v[0:1], off
	v_lshl_add_u64 v[0:1], v[2:3], 0, s[92:93]
	s_mov_b32 m0, s49
	s_addc_u32 s3, s25, 0
	global_load_lds_dwordx4 v[0:1], off
	s_add_i32 m0, s21, 0x1c000
	v_lshl_add_u64 v[0:1], s[2:3], 0, v[192:193]
	global_load_lds_dwordx4 v[0:1], off
	v_lshl_add_u64 v[0:1], s[2:3], 0, v[156:157]
	s_add_i32 m0, s21, 0x1e000
	s_cmpk_lt_u32 s10, 0x100
	global_load_lds_dwordx4 v[0:1], off
	s_waitcnt vmcnt(8)
	s_barrier
	v_and_b32_e32 v0, 15, v8
	v_and_b32_e32 v1, 48, v8
	v_lshl_or_b32 v0, v0, 6, v1
	v_lshlrev_b32_e32 v1, 2, v8
	v_and_b32_e32 v1, 32, v1
	v_bitop3_b32 v2, v0, s11, v1 bitop3:0xde
	v_bitop3_b32 v212, s13, v0, v1 bitop3:0xf6
	v_lshlrev_b32_e32 v0, 15, v13
	v_and_b32_e32 v0, 0xffff0000, v0
	v_lshl_add_u32 v0, v12, 12, v0
	v_and_b32_e32 v1, 1, v13
	v_lshl_or_b32 v0, v1, 6, v0
	v_lshl_add_u32 v162, v14, 1, v0
	v_lshlrev_b32_e32 v0, 15, v9
	v_and_b32_e32 v0, 0xffff0000, v0
	s_waitcnt vmcnt(6)
	v_lshl_add_u32 v0, v10, 12, v0
	v_and_b32_e32 v1, 1, v9
	v_lshl_or_b32 v0, v1, 6, v0
	s_cselect_b64 s[10:11], -1, 0
	s_lshl_b32 s50, s12, 6
	s_lshl_b32 s51, s1, 5
	v_mov_b32_e32 v163, v193
	v_lshl_add_u32 v164, v11, 1, v0
	v_mov_b32_e32 v165, v193
	s_mov_b32 s52, 0
	v_add_u32_e32 v213, 0, v2
	s_barrier
	s_branch .LBB0_1039

; #define PG8_STAGE(bufoff, gbase, voff) do { _Pragma("unroll") for (int _i = 0; _i < 2; ++_i) \
;         __builtin_amdgcn_global_load_lds((const unsigned*)((const char*)(gbase) + (voff)[_i]), (LAS unsigned*)(lds + (bufoff) + ldsw + _i * 8192), 16, 0, 0); } while (0)
; #define PG8_WAIT_V(n) asm volatile("s_waitcnt vmcnt(" #n ")" ::: "memory")
; #define PG8_BAR __builtin_amdgcn_s_barrier()
; template <class EpiT, class Sched>
; __device__ __forceinline__ void gemm_phase(LAS unsigned char* lds, const Gemm g, const Sched& S, const EpiT& E, int wv) {
;     ...
;     const int foff = lds_byte(fr, fq * 8);
;     const int aoff = wr * 8192 + foff, boff = wc * 4096 + foff;
;     ...
;     const char* cA = (const char*)g.A + (size_t)cur.pm * tstepA + (size_t)(cur.pn >> g.zshift) * g.zA; const char* cB = (const char*)g.Bt + (size_t)cur.pn * tstepB;
;     PG8_STAGE(PG8_SB(0, 0), cB, voffB); PG8_STAGE(PG8_SB(0, 1), cB + hstepB, voffB); PG8_STAGE(PG8_SA(0, 0), cA, voffA); PG8_STAGE(PG8_SA(0, 1), cA + hstepA, voffA);
;     if (wr == 1) PG8_BAR;
;     PG8_WAIT_V(2); PG8_BAR;
;     PG8_STAGE(PG8_SB(1, 0), cB + kstep, voffB); PG8_STAGE(PG8_SA(1, 0), cA + kstep, voffA); PG8_STAGE(PG8_SB(1, 1), cB + hstepB + kstep, voffB);
;     PG8_WAIT_V(6); PG8_BAR;
.LBB0_1148:
	s_mul_i32 s18, s90, 0x12000
	s_mul_hi_u32 s1, s90, 0x12000
	s_add_u32 s18, s10, s18
	s_addc_u32 s1, s11, s1
	s_add_u32 s56, s18, 0x310a000
	s_addc_u32 s57, s1, 0
	s_add_u32 s18, s10, 0x3c00000
	s_addc_u32 s19, s11, 0
	s_and_b32 s1, s3, 3
	s_lshl_b32 s3, s2, 13
	s_lshl_b32 s21, s1, 12
	v_readlane_b32 s22, v255, 40
	s_add_u32 s22, s10, s22
	v_readlane_b32 s23, v255, 39
	s_addc_u32 s23, s11, s23
	s_add_u32 s58, s22, 0x3002000
	s_addc_u32 s59, s23, 0
	s_add_i32 m0, s27, 0x18000
	v_lshl_add_u64 v[6:7], v[6:7], 0, s[92:93]
	global_load_lds_dwordx4 v[6:7], off
	v_lshl_add_u64 v[4:5], v[4:5], 0, s[92:93]
	s_add_i32 m0, s27, 0x1a000
	s_add_i32 s62, s27, 0x8000
	s_add_i32 s63, s27, 0xa000
	global_load_lds_dwordx4 v[4:5], off
	v_lshl_add_u64 v[0:1], v[0:1], 0, s[92:93]
	s_mov_b32 m0, s62
	s_add_u32 s22, s38, 0x100080
	global_load_lds_dwordx4 v[0:1], off
	v_lshl_add_u64 v[0:1], v[2:3], 0, s[92:93]
	s_mov_b32 m0, s63
	s_addc_u32 s23, s39, 0
	global_load_lds_dwordx4 v[0:1], off
	s_add_i32 m0, s27, 0x1c000
	v_lshl_add_u64 v[0:1], s[22:23], 0, v[192:193]
	global_load_lds_dwordx4 v[0:1], off
	v_lshl_add_u64 v[0:1], s[22:23], 0, v[172:173]
	s_add_i32 m0, s27, 0x1e000
	s_cmpk_lt_u32 s20, 0x100
	global_load_lds_dwordx4 v[0:1], off
	s_waitcnt vmcnt(8)
	s_barrier
	v_and_b32_e32 v0, 15, v8
	v_and_b32_e32 v1, 48, v8
	v_lshl_or_b32 v0, v0, 6, v1
	v_lshlrev_b32_e32 v1, 2, v8
	v_and_b32_e32 v1, 32, v1
	v_bitop3_b32 v2, v0, s3, v1 bitop3:0xde
	v_bitop3_b32 v240, s21, v0, v1 bitop3:0xf6
	v_lshlrev_b32_e32 v0, 14, v9
	v_and_b32_e32 v0, 0xffff8000, v0
	s_cselect_b64 s[20:21], -1, 0
	s_lshl_b32 s67, s2, 6
	s_lshl_b32 s72, s1, 5
	s_ashr_i32 s73, s47, 31
	s_lshl_b32 s1, s1, 2
	v_lshl_add_u32 v0, v10, 11, v0
	v_and_b32_e32 v1, 1, v9
	s_add_u32 s1, s10, s1
	v_lshl_or_b32 v0, v1, 6, v0
	s_addc_u32 s2, s11, 0
	v_lshl_add_u32 v174, v11, 1, v0
	v_lshlrev_b32_e32 v0, 14, v12
	s_add_u32 s79, s1, 0x1fa00000
	v_and_b32_e32 v0, 0xffff8000, v0
	s_waitcnt vmcnt(6)
	s_addc_u32 s82, s2, 0
	v_lshl_add_u32 v0, v13, 11, v0
	v_and_b32_e32 v1, 1, v12
	s_cmp_lg_u64 s[10:11], 0
	v_lshl_or_b32 v0, v1, 6, v0
	s_cselect_b64 s[10:11], -1, 0
	v_mov_b32_e32 v175, v193
	v_lshl_add_u32 v176, v14, 1, v0
	v_mov_b32_e32 v177, v193
	s_mov_b32 s88, 0
	v_add_u32_e32 v241, 0, v2
	s_barrier
	s_branch .LBB0_1151

; #define PG8_STAGE(bufoff, gbase, voff) do { _Pragma("unroll") for (int _i = 0; _i < 2; ++_i) \
;         __builtin_amdgcn_global_load_lds((const unsigned*)((const char*)(gbase) + (voff)[_i]), (LAS unsigned*)(lds + (bufoff) + ldsw + _i * 8192), 16, 0, 0); } while (0)
; #define PG8_WAIT_V(n) asm volatile("s_waitcnt vmcnt(" #n ")" ::: "memory")
; #define PG8_BAR __builtin_amdgcn_s_barrier()
; template <class EpiT, class Sched>
; __device__ __forceinline__ void gemm_phase(LAS unsigned char* lds, const Gemm g, const Sched& S, const EpiT& E, int wv) {
;     ...
;     const int foff = lds_byte(fr, fq * 8);
;     const int aoff = wr * 8192 + foff, boff = wc * 4096 + foff;
;     ...
;     const char* cA = (const char*)g.A + (size_t)cur.pm * tstepA + (size_t)(cur.pn >> g.zshift) * g.zA; const char* cB = (const char*)g.Bt + (size_t)cur.pn * tstepB;
;     PG8_STAGE(PG8_SB(0, 0), cB, voffB); PG8_STAGE(PG8_SB(0, 1), cB + hstepB, voffB); PG8_STAGE(PG8_SA(0, 0), cA, voffA); PG8_STAGE(PG8_SA(0, 1), cA + hstepA, voffA);
;     if (wr == 1) PG8_BAR;
;     PG8_WAIT_V(2); PG8_BAR;
;     PG8_STAGE(PG8_SB(1, 0), cB + kstep, voffB); PG8_STAGE(PG8_SA(1, 0), cA + kstep, voffA); PG8_STAGE(PG8_SB(1, 1), cB + hstepB + kstep, voffB);
;     PG8_WAIT_V(6); PG8_BAR;
.LBB0_1265:
	s_add_u32 s6, s6, 0x16a00000
	s_addc_u32 s7, s7, 0
	s_and_b32 s2, s2, 3
	s_add_i32 m0, s19, 0x18000
	v_lshl_add_u64 v[6:7], v[6:7], 0, s[92:93]
	s_lshl_b32 s10, s3, 13
	s_lshl_b32 s11, s2, 12
	global_load_lds_dwordx4 v[6:7], off
	v_lshl_add_u64 v[4:5], v[4:5], 0, s[92:93]
	s_add_i32 m0, s19, 0x1a000
	s_add_i32 s40, s19, 0x8000
	s_add_i32 s41, s19, 0xa000
	global_load_lds_dwordx4 v[4:5], off
	v_lshl_add_u64 v[2:3], v[2:3], 0, s[92:93]
	s_mov_b32 m0, s40
	s_add_u32 s8, s24, 0x40080
	global_load_lds_dwordx4 v[2:3], off
	v_lshl_add_u64 v[0:1], v[0:1], 0, s[92:93]
	s_mov_b32 m0, s41
	s_addc_u32 s9, s25, 0
	global_load_lds_dwordx4 v[0:1], off
	s_add_i32 m0, s19, 0x1c000
	v_lshl_add_u64 v[0:1], s[8:9], 0, v[192:193]
	global_load_lds_dwordx4 v[0:1], off
	v_lshl_add_u64 v[0:1], s[8:9], 0, v[140:141]
	s_add_i32 m0, s19, 0x1e000
	s_cmpk_lt_u32 s12, 0x100
	global_load_lds_dwordx4 v[0:1], off
	s_waitcnt vmcnt(8)
	s_barrier
	v_and_b32_e32 v0, 15, v8
	v_and_b32_e32 v1, 48, v8
	v_lshl_or_b32 v0, v0, 6, v1
	v_lshlrev_b32_e32 v1, 2, v8
	v_and_b32_e32 v1, 32, v1
	v_bitop3_b32 v2, v0, s10, v1 bitop3:0xde
	v_bitop3_b32 v158, s11, v0, v1 bitop3:0xf6
	v_lshlrev_b32_e32 v0, 14, v9
	v_and_b32_e32 v0, 0xffff8000, v0
	v_lshl_add_u32 v0, v10, 11, v0
	v_and_b32_e32 v1, 1, v9
	v_lshl_or_b32 v0, v1, 6, v0
	v_lshl_add_u32 v142, v11, 1, v0
	v_lshlrev_b32_e32 v0, 14, v12
	v_and_b32_e32 v0, 0xffff8000, v0
	s_waitcnt vmcnt(6)
	v_lshl_add_u32 v0, v13, 11, v0
	v_and_b32_e32 v1, 1, v12
	v_lshl_or_b32 v0, v1, 6, v0
	s_cselect_b64 s[8:9], -1, 0
	s_lshl_b32 s47, s3, 6
	s_lshl_b32 s48, s2, 5
	v_mov_b32_e32 v143, v193
	v_lshl_add_u32 v144, v14, 1, v0
	v_mov_b32_e32 v145, v193
	s_mov_b32 s50, 0
	v_add_u32_e32 v159, 0, v2
	s_barrier
	s_branch .LBB0_1268

; #define PG8_STAGE(bufoff, gbase, voff) do { _Pragma("unroll") for (int _i = 0; _i < 2; ++_i) \
;         __builtin_amdgcn_global_load_lds((const unsigned*)((const char*)(gbase) + (voff)[_i]), (LAS unsigned*)(lds + (bufoff) + ldsw + _i * 8192), 16, 0, 0); } while (0)
; #define PG8_WAIT_V(n) asm volatile("s_waitcnt vmcnt(" #n ")" ::: "memory")
; #define PG8_BAR __builtin_amdgcn_s_barrier()
; template <class EpiT, class Sched>
; __device__ __forceinline__ void gemm_phase(LAS unsigned char* lds, const Gemm g, const Sched& S, const EpiT& E, int wv) {
;     ...
;     const int foff = lds_byte(fr, fq * 8);
;     const int aoff = wr * 8192 + foff, boff = wc * 4096 + foff;
;     ...
;     const char* cA = (const char*)g.A + (size_t)cur.pm * tstepA + (size_t)(cur.pn >> g.zshift) * g.zA; const char* cB = (const char*)g.Bt + (size_t)cur.pn * tstepB;
;     PG8_STAGE(PG8_SB(0, 0), cB, voffB); PG8_STAGE(PG8_SB(0, 1), cB + hstepB, voffB); PG8_STAGE(PG8_SA(0, 0), cA, voffA); PG8_STAGE(PG8_SA(0, 1), cA + hstepA, voffA);
;     if (wr == 1) PG8_BAR;
;     PG8_WAIT_V(2); PG8_BAR;
;     PG8_STAGE(PG8_SB(1, 0), cB + kstep, voffB); PG8_STAGE(PG8_SA(1, 0), cA + kstep, voffA); PG8_STAGE(PG8_SB(1, 1), cB + hstepB + kstep, voffB);
;     PG8_WAIT_V(6); PG8_BAR;
.LBB0_1329:
	s_mul_i32 s12, s90, 0xd800
	s_mov_b32 s13, s77
	s_add_u32 s43, s10, 0x3400000
	s_addc_u32 s44, s11, 0
	s_lshl_b64 s[12:13], s[12:13], 2
	s_add_u32 s3, s10, s12
	s_addc_u32 s12, s11, s13
	s_mul_i32 s14, s90, 0x4800
	s_mov_b32 s15, s77
	s_add_u32 s46, s3, 0x3005000
	s_addc_u32 s47, s12, 0
	s_lshl_b64 s[12:13], s[14:15], 2
	s_add_u32 s3, s10, s12
	s_addc_u32 s12, s11, s13
	s_add_u32 s48, s3, 0x3113000
	s_addc_u32 s49, s12, 0
	s_add_u32 s12, s10, 0x3c00000
	s_addc_u32 s13, s11, 0
	s_and_b32 s1, s1, 3
	s_add_i32 m0, s38, 0x18000
	v_lshl_add_u64 v[6:7], v[6:7], 0, s[92:93]
	s_lshl_b32 s3, s0, 13
	s_lshl_b32 s16, s1, 12
	global_load_lds_dwordx4 v[6:7], off
	v_lshl_add_u64 v[4:5], v[4:5], 0, s[92:93]
	s_add_i32 m0, s38, 0x1a000
	s_add_i32 s50, s38, 0x8000
	s_add_i32 s51, s38, 0xa000
	global_load_lds_dwordx4 v[4:5], off
	v_lshl_add_u64 v[0:1], v[0:1], 0, s[92:93]
	s_mov_b32 m0, s50
	s_add_u32 s14, s24, 0x100080
	global_load_lds_dwordx4 v[0:1], off
	v_lshl_add_u64 v[0:1], v[2:3], 0, s[92:93]
	s_mov_b32 m0, s51
	s_addc_u32 s15, s25, 0
	global_load_lds_dwordx4 v[0:1], off
	s_add_i32 m0, s38, 0x1c000
	v_lshl_add_u64 v[0:1], s[14:15], 0, v[192:193]
	global_load_lds_dwordx4 v[0:1], off
	v_lshl_add_u64 v[0:1], s[14:15], 0, v[172:173]
	s_add_i32 m0, s38, 0x1e000
	s_cmpk_lt_u32 s2, 0x100
	global_load_lds_dwordx4 v[0:1], off
	s_waitcnt vmcnt(8)
	s_barrier
	v_and_b32_e32 v0, 15, v8
	v_and_b32_e32 v1, 48, v8
	v_lshl_or_b32 v0, v0, 6, v1
	v_lshlrev_b32_e32 v1, 2, v8
	v_and_b32_e32 v1, 32, v1
	v_bitop3_b32 v2, v0, s3, v1 bitop3:0xde
	v_bitop3_b32 v214, s16, v0, v1 bitop3:0xf6
	v_lshlrev_b32_e32 v0, 16, v9
	v_and_b32_e32 v0, 0xfffe0000, v0
	v_lshl_add_u32 v0, v10, 13, v0
	v_and_b32_e32 v1, 1, v9
	v_lshl_or_b32 v0, v1, 6, v0
	s_cselect_b64 s[14:15], -1, 0
	s_lshl_b32 s52, s0, 6
	s_lshl_b32 s53, s1, 5
	s_ashr_i32 s54, s28, 31
	s_lshl_b32 s0, s1, 2
	v_lshl_add_u32 v174, v11, 1, v0
	v_lshlrev_b32_e32 v0, 16, v12
	s_add_u32 s0, s10, s0
	v_and_b32_e32 v0, 0xfffe0000, v0
	s_waitcnt vmcnt(6)
	s_addc_u32 s1, s11, 0
	v_lshl_add_u32 v0, v13, 13, v0
	v_and_b32_e32 v1, 1, v12
	s_add_u32 s55, s0, 0x1fa00000
	v_lshl_or_b32 v0, v1, 6, v0
	s_addc_u32 s56, s1, 0
	v_mov_b32_e32 v175, v193
	v_lshl_add_u32 v176, v14, 1, v0
	v_mov_b32_e32 v177, v193
	s_mov_b32 s57, 0
	v_add_u32_e32 v215, 0, v2
	s_barrier
	s_branch .LBB0_1332
